# v032
# speedup vs baseline: 1.0497x; 1.0009x over previous
; __device__ __forceinline__ int otid(int wvs) { int l; asm volatile("v_mbcnt_lo_u32_b32 %0, -1, 0\n\tv_mbcnt_hi_u32_b32 %0, -1, %0" : "=v"(l)); return wvs * 64 + l; }
; __device__ __forceinline__ int v_rd_base(int lane) { return ((lane & 3) << 3) | (((lane >> 2) & 3) << 6) | (((lane >> 4) & 1) << 5) | (((lane >> 5) & 1) << 8); }
; #define ISSUE_K(t, slot) do { const char* kg_ = (const char*)(Kh + (long)(t) * (KVBLK * 192)); char* kl_ = K_lds + (slot) * SHM_K + tid * 16; \
;     DMA16(kg_ + kso0, kl_); DMA16(kg_ + kso1, kl_ + 8192); DMA16(kg_ + kso2, kl_ + 16384); } while (0)
; __device__ __forceinline__ void attn_body(const u16* __restrict__ Qb, const u16* __restrict__ Kh, const u16* __restrict__ Vh,
;                                           u16* __restrict__ Ob, int seq, int wvs) {
;     ...
;   const int tid = otid(wvs), wid = tid >> 6, lane = tid & 63, r32 = lane & 31, hi = lane >> 5;
;   char* V_lds = lds; char* K_lds = lds + 3 * SHM_V;
;   float* ws = (float*)(lds + 3 * SHM_V + 3 * SHM_K) + wid * 64; float* li_l = ws; float* al_l = ws + 32;
;   float m_reg = -1e30f, l_reg = 0; f32x16 o[4] = {}; bf16x8 qr[12];
;   const u16* Qw = Qb + (long)(wid * QBLK + r32) * 192 + hi * 8;
; #pragma unroll
;   for (int d0 = 0; d0 < 12; ++d0) qr[d0] = *reinterpret_cast<const bf16x8*>(Qw + d0 * 16);
;   unsigned kso0, kso1, kso2, vso0, vso1;
;   { int p = tid * 16, row = p / 384, pc = p - row * 384; kso0 = row * 384 + (pc ^ (((row >> 1) & 7) << 4));
;     p = 8192 + tid * 16; row = p / 384; pc = p - row * 384; kso1 = row * 384 + (pc ^ (((row >> 1) & 7) << 4));
;     p = 16384 + tid * 16; row = p / 384; pc = p - row * 384; kso2 = row * 384 + (pc ^ (((row >> 1) & 7) << 4)); }
;   { int p = tid * 16, sub = p >> 9, w = p & 511, kk = (sub >> 2) * 8 + (w >> 6), c = (sub & 3) * 32 + ((w & 63) >> 1);
;     int k = (kk & ~0xC) | ((kk & 4) << 1) | ((kk & 8) >> 1); vso0 = k * 256 + c * 2;
;     p = 8192 + tid * 16; sub = p >> 9; w = p & 511; kk = (sub >> 2) * 8 + (w >> 6); c = (sub & 3) * 32 + ((w & 63) >> 1);
;     k = (kk & ~0xC) | ((kk & 4) << 1) | ((kk & 8) >> 1); vso1 = k * 256 + c * 2; }
;   const int vb0 = (int)(uintptr_t)V_lds + v_rd_base(lane);
;     ...
;   f32x16 pA0, pA1, pB0, pB1; float mnA, mnB, alA, alB; bf16x8 pa0, pa1, pa2, pa3; const int NT = seq / KVBLK;
;   ISSUE_K(0, 0); ISSUE_V(0, 0); ISSUE_K(1, 1);
;   TBAR(5);
.LBB0_329:
	s_and_b64 vcc, exec, s[10:11]
	s_cbranch_vccz .LBB0_767
	v_mbcnt_lo_u32_b32 v2, -1, 0
	v_mbcnt_hi_u32_b32 v2, -1, v2
	s_movk_i32 s4, 0xffe0
	v_add_u32_e32 v3, s69, v2
	v_ashrrev_i32_e32 v4, 1, v3
	v_bfi_b32 v5, s4, v4, v2
	v_readlane_b32 s4, v255, 0
	v_readlane_b32 s5, v255, 1
	v_bfe_u32 v186, v2, 5, 1
	v_lshlrev_b32_e32 v160, 4, v186
	v_mov_b64_e32 v[0:1], s[4:5]
	v_mad_i64_i32 v[0:1], s[4:5], v5, s56, v[0:1]
	v_lshl_add_u64 v[0:1], v[0:1], 0, v[160:161]
	s_mov_b32 s4, 0x2aaaaaab
	flat_load_dwordx4 v[140:143], v[0:1]
	flat_load_dwordx4 v[136:139], v[0:1] offset:32
	flat_load_dwordx4 v[132:135], v[0:1] offset:64
	flat_load_dwordx4 v[128:131], v[0:1] offset:96
	flat_load_dwordx4 v[124:127], v[0:1] offset:128
	flat_load_dwordx4 v[120:123], v[0:1] offset:160
	flat_load_dwordx4 v[116:119], v[0:1] offset:192
	flat_load_dwordx4 v[112:115], v[0:1] offset:224
	flat_load_dwordx4 v[108:111], v[0:1] offset:256
	flat_load_dwordx4 v[104:107], v[0:1] offset:288
	flat_load_dwordx4 v[100:103], v[0:1] offset:320
	flat_load_dwordx4 v[96:99], v[0:1] offset:352
	v_mul_hi_i32 v1, v3, s4
	v_lshrrev_b32_e32 v5, 31, v1
	v_ashrrev_i32_e32 v1, 2, v1
	v_add_u32_e32 v1, v1, v5
	v_lshlrev_b32_e32 v0, 4, v3
	v_mul_lo_u32 v5, v1, s56
	v_lshlrev_b32_e32 v1, 3, v1
	v_sub_u32_e32 v6, v0, v5
	v_and_b32_e32 v1, 0x70, v1
	v_xad_u32 v48, v6, v1, v5
	v_add_u32_e32 v1, 0x2000, v0
	v_mul_hi_i32 v5, v1, s4
	v_lshrrev_b32_e32 v6, 31, v5
	v_ashrrev_i32_e32 v5, 6, v5
	v_add_u32_e32 v5, v5, v6
	v_mul_i32_i24_e32 v6, 0x180, v5
	v_lshlrev_b32_e32 v5, 3, v5
	v_sub_u32_e32 v7, v1, v6
	v_and_b32_e32 v5, 0x70, v5
	v_xad_u32 v50, v7, v5, v6
	v_add_u32_e32 v5, 0x4000, v0
	v_mul_hi_i32 v6, v5, s4
	v_lshrrev_b32_e32 v7, 31, v6
	v_ashrrev_i32_e32 v6, 6, v6
	v_add_u32_e32 v6, v6, v7
	v_mul_i32_i24_e32 v7, 0x180, v6
	v_lshlrev_b32_e32 v6, 3, v6
	v_sub_u32_e32 v5, v5, v7
	v_and_b32_e32 v6, 0x70, v6
	v_xad_u32 v52, v5, v6, v7
	v_ashrrev_i32_e32 v5, 4, v3
	v_ashrrev_i32_e32 v1, 8, v1
	v_and_b32_e32 v63, -16, v5
	v_lshrrev_b32_e32 v6, 1, v3
	v_lshrrev_b32_e32 v5, 1, v5
	v_lshrrev_b32_e32 v7, 1, v1
	v_and_b32_e32 v64, 8, v6
	v_and_b32_e32 v65, 4, v5
	v_lshlrev_b32_e32 v6, 1, v3
	v_and_b32_e32 v7, 4, v7
	v_bfe_u32 v62, v3, 2, 2
	v_or_b32_e32 v5, v65, v63
	v_and_b32_e32 v66, 0xc0, v6
	v_and_b32_e32 v67, 48, v0
	v_and_or_b32 v68, v1, -16, v7
	v_or3_b32 v5, v5, v62, v64
	v_or_b32_e32 v6, v67, v66
	v_or3_b32 v1, v68, v62, v64
	v_add_u32_e32 v192, 0, v0
	v_lshl_or_b32 v5, v5, 8, v6
	v_bfe_u32 v252, v5, 10, 1
	v_bfe_u32 v253, v5, 11, 1
	v_xor_b32_e32 v252, v252, v253
	v_mul_u32_u24_e32 v252, 0xc00, v252
	v_xor_b32_e32 v5, v5, v252
	v_lshl_or_b32 v1, v1, 8, v6
	v_bfe_u32 v252, v1, 10, 1
	v_bfe_u32 v253, v1, 11, 1
	v_xor_b32_e32 v252, v252, v253
	v_mul_u32_u24_e32 v252, 0xc00, v252
	v_xor_b32_e32 v1, v1, v252
	v_add_u32_e32 v6, 0xc000, v192
	s_add_i32 s6, 0, 0x1e000
	v_readfirstlane_b32 s5, v6
	v_add_u32_e32 v6, 0xe000, v192
	s_mov_b32 m0, s5
	v_readfirstlane_b32 s5, v6
	v_add_u32_e32 v6, 0x10000, v192
	global_load_lds_dwordx4 v48, s[86:87]
	s_mov_b32 m0, s5
	v_readfirstlane_b32 s5, v6
	global_load_lds_dwordx4 v50, s[86:87]
	s_mov_b32 m0, s5
	v_readfirstlane_b32 s5, v192
	v_add_u32_e32 v6, 0x2000, v192
	s_cmp_lg_u32 0, -1
	global_load_lds_dwordx4 v52, s[86:87]
	s_mov_b32 m0, s5
	v_readfirstlane_b32 s5, v6
	s_cselect_b32 s4, 0, 0
	global_load_lds_dwordx4 v5, s[28:29]
	s_mov_b32 m0, s5
	s_add_i32 s5, 0, 0x12000
	v_add_u32_e32 v6, s5, v0
	v_add_u32_e32 v7, 0x2000, v6
	v_readfirstlane_b32 s5, v6
	global_load_lds_dwordx4 v1, s[28:29]
	s_mov_b32 m0, s5
	v_readfirstlane_b32 s5, v7
	v_add_u32_e32 v6, 0x4000, v6
	global_load_lds_dwordx4 v48, s[54:55]
	s_mov_b32 m0, s5
	v_readfirstlane_b32 s5, v6
	global_load_lds_dwordx4 v50, s[54:55]
	s_mov_b32 m0, s5
	v_and_b32_e32 v69, 63, v2
	global_load_lds_dwordx4 v52, s[54:55]
	v_and_b32_e32 v3, 0x3fffffc0, v3
	v_and_b32_e32 v164, 0xffffffe0, v4
	v_lshlrev_b32_e32 v4, 4, v2
	v_lshl_add_u32 v165, v3, 2, s6
	v_lshlrev_b32_e32 v3, 3, v69
	v_and_b32_e32 v4, 0xc0, v4
	v_lshlrev_b32_e32 v6, 1, v2
	v_and_or_b32 v4, v3, 24, v4
	v_and_b32_e32 v6, 32, v6
	v_and_b32_e32 v3, 0x100, v3
	s_waitcnt vmcnt(5) lgkmcnt(0)
	v_or3_b32 v3, v4, v6, v3
	v_and_b32_e32 v187, 31, v2
	s_mov_b32 s31, 1
	s_mov_b32 s30, 4
	s_mov_b32 s12, 0
	v_add_u32_e32 v190, s4, v3
	v_mov_b32_e32 v49, v161
	v_mov_b32_e32 v51, v161
	v_mov_b32_e32 v53, v161
	s_barrier
	s_cmp_lt_u32 s69, 0x100
	s_cbranch_scc1 .Latt_prio_skip
	s_setprio 1
; #define ISSUE_K(t, slot) do { const char* kg_ = (const char*)(Kh + (long)(t) * (KVBLK * 192)); char* kl_ = K_lds + (slot) * SHM_K + tid * 16; \
;     DMA16(kg_ + kso0, kl_); DMA16(kg_ + kso1, kl_ + 8192); DMA16(kg_ + kso2, kl_ + 16384); } while (0)
; #define ISSUE_V(t, slot) do { const char* vg_ = (const char*)(Vh + (long)(t) * (KVBLK * 128)); char* vl_ = V_lds + (slot) * SHM_V + tid * 16; \
;     DMA16(vg_ + vso0, vl_); DMA16(vg_ + vso1, vl_ + 8192); } while (0)
; #define TBAR(n) do { asm volatile("s_waitcnt vmcnt(" #n ") lgkmcnt(0)" ::: "memory"); __builtin_amdgcn_s_barrier(); SBAR(); } while (0)
; __device__ __forceinline__ void qkt(f32x16& p0, f32x16& p1, const char* Ks, const bf16x8* qr, int r32, int hi) {
;   p0 = f32x16{}; p1 = f32x16{};
; #pragma unroll
;   for (int d0 = 0; d0 < 12; ++d0) { int cb = (d0 * 16 + hi * 8) * 2;
;     bf16x8 b0 = *reinterpret_cast<const bf16x8*>(Ks + KSWZ(r32, cb));
;     bf16x8 b1 = *reinterpret_cast<const bf16x8*>(Ks + KSWZ(32 + r32, cb));
;     p0 = __builtin_amdgcn_mfma_f32_32x32x16_bf16(b0, qr[d0], p0, 0, 0, 0);
;     p1 = __builtin_amdgcn_mfma_f32_32x32x16_bf16(b1, qr[d0], p1, 0, 0, 0); }
; }
; __device__ __forceinline__ void attn_body(const u16* __restrict__ Qb, const u16* __restrict__ Kh, const u16* __restrict__ Vh,
;                                           u16* __restrict__ Ob, int seq, int wvs) {
;     ...
;   f32x16 pA0, pA1, pB0, pB1; float mnA, mnB, alA, alB; bf16x8 pa0, pa1, pa2, pa3; const int NT = seq / KVBLK;
;   ISSUE_K(0, 0); ISSUE_V(0, 0); ISSUE_K(1, 1);
;   TBAR(5);
;   ISSUE_K(2, 2); ISSUE_V(1, 1);
;   qkt(pA0, pA1, K_lds, qr, r32, hi); partialSM(pA0, pA1, m_reg, mnA, alA);
.Latt_prio_skip:
	v_add_u32_e32 v0, s83, v0
	v_add_u32_e32 v3, 0x2000, v0
	v_readfirstlane_b32 s4, v0
	s_mov_b32 m0, s4
	v_readfirstlane_b32 s4, v3
	v_add_u32_e32 v0, 0x4000, v0
	global_load_lds_dwordx4 v48, s[44:45]
	s_mov_b32 m0, s4
	v_readfirstlane_b32 s4, v0
	v_add_u32_e32 v0, 0x4000, v192
	global_load_lds_dwordx4 v50, s[44:45]
	s_mov_b32 m0, s4
	v_readfirstlane_b32 s4, v0
	v_add_u32_e32 v0, 0x6000, v192
	global_load_lds_dwordx4 v52, s[44:45]
	s_mov_b32 m0, s4
	v_readfirstlane_b32 s4, v0
	v_lshlrev_b32_e32 v0, 3, v2
	v_mul_u32_u24_e32 v8, 0x180, v187
	v_and_b32_e32 v9, 0x70, v0
	global_load_lds_dwordx4 v5, s[50:51]
	s_mov_b32 m0, s4
	v_bitop3_b32 v193, v160, v8, v9 bitop3:0xde
	global_load_lds_dwordx4 v1, s[50:51]
	v_add_u32_e32 v4, 0, v193
	ds_read_b128 v[0:3], v4 offset:49152
	ds_read_b128 v[4:7], v4 offset:61440
	s_waitcnt vmcnt(0) lgkmcnt(0)
	v_mfma_f32_32x32x16_bf16 v[16:31], v[0:3], v[140:143], 0
	v_or_b32_e32 v0, 32, v160
	v_bitop3_b32 v199, v0, v8, v9 bitop3:0xde
	s_mov_b32 s13, s12
	s_mov_b32 s14, s12
	s_mov_b32 s15, s12
	s_mov_b32 s16, s12
	s_mov_b32 s17, s12
	v_mfma_f32_32x32x16_bf16 v[32:47], v[4:7], v[140:143], 0
	v_add_u32_e32 v4, 0, v199
	ds_read_b128 v[0:3], v4 offset:49152
	ds_read_b128 v[4:7], v4 offset:61440
	s_mov_b32 s18, s12
	s_mov_b32 s19, s12
	s_mov_b32 s20, s12
	s_mov_b32 s21, s12
	s_mov_b32 s22, s12
	s_waitcnt lgkmcnt(1)
	v_mfma_f32_32x32x16_bf16 v[16:31], v[0:3], v[136:139], v[16:31]
	v_or_b32_e32 v0, 64, v160
	v_bitop3_b32 v200, v0, v8, v9 bitop3:0xde
	s_mov_b32 s23, s12
	s_mov_b32 s24, s12
	s_mov_b32 s25, s12
	s_mov_b32 s26, s12
	s_mov_b32 s27, s12
	s_waitcnt lgkmcnt(0)
	v_mfma_f32_32x32x16_bf16 v[32:47], v[4:7], v[136:139], v[32:47]
	v_add_u32_e32 v4, 0, v200
	ds_read_b128 v[0:3], v4 offset:49152
	ds_read_b128 v[4:7], v4 offset:61440
	v_mov_b32_e32 v168, v52
	v_mov_b32_e32 v167, v50
	v_mov_b32_e32 v166, v48
	s_add_u32 s98, s80, s48
	s_addc_u32 s99, s81, s49
	s_add_u32 s98, s98, s70
	s_addc_u32 s99, s99, s71
	v_cmp_gt_u32_e64 s[6:7], 32, v69
	v_lshl_add_u32 v188, v187, 2, v165
	s_waitcnt lgkmcnt(1)
	v_mfma_f32_32x32x16_bf16 v[16:31], v[0:3], v[132:135], v[16:31]
	v_or_b32_e32 v0, 0x60, v160
	v_bitop3_b32 v202, v0, v8, v9 bitop3:0xde
	v_mov_b32_e32 v189, 0
	s_waitcnt lgkmcnt(0)
	v_mfma_f32_32x32x16_bf16 v[32:47], v[4:7], v[132:135], v[32:47]
	v_add_u32_e32 v4, 0, v202
	ds_read_b128 v[0:3], v4 offset:49152
	ds_read_b128 v[4:7], v4 offset:61440
	s_waitcnt lgkmcnt(1)
	v_mfma_f32_32x32x16_bf16 v[16:31], v[0:3], v[128:131], v[16:31]
	v_or_b32_e32 v0, 0x80, v160
	v_xad_u32 v207, v0, v9, v8
	v_add_u32_e32 v10, 0, v207
	s_waitcnt lgkmcnt(0)
	v_mfma_f32_32x32x16_bf16 v[32:47], v[4:7], v[128:131], v[32:47]
	ds_read_b128 v[0:3], v10 offset:49152
	ds_read_b128 v[4:7], v10 offset:61440
	s_waitcnt lgkmcnt(1)
	v_mfma_f32_32x32x16_bf16 v[16:31], v[0:3], v[124:127], v[16:31]
	v_or_b32_e32 v0, 0xa0, v160
	v_xad_u32 v203, v0, v9, v8
	v_add_u32_e32 v10, 0, v203
	s_waitcnt lgkmcnt(0)
	v_mfma_f32_32x32x16_bf16 v[32:47], v[4:7], v[124:127], v[32:47]
	ds_read_b128 v[0:3], v10 offset:49152
	ds_read_b128 v[4:7], v10 offset:61440
	s_waitcnt lgkmcnt(1)
	v_mfma_f32_32x32x16_bf16 v[16:31], v[0:3], v[120:123], v[16:31]
	v_or_b32_e32 v0, 0xc0, v160
	v_xad_u32 v201, v0, v9, v8
	v_add_u32_e32 v10, 0, v201
	s_waitcnt lgkmcnt(0)
	v_mfma_f32_32x32x16_bf16 v[32:47], v[4:7], v[120:123], v[32:47]
	ds_read_b128 v[0:3], v10 offset:49152
	ds_read_b128 v[4:7], v10 offset:61440
	s_waitcnt lgkmcnt(1)
	v_mfma_f32_32x32x16_bf16 v[16:31], v[0:3], v[116:119], v[16:31]
	v_or_b32_e32 v0, 0xe0, v160
	v_xad_u32 v198, v0, v9, v8
	v_add_u32_e32 v10, 0, v198
	s_waitcnt lgkmcnt(0)
	v_mfma_f32_32x32x16_bf16 v[32:47], v[4:7], v[116:119], v[32:47]
	ds_read_b128 v[0:3], v10 offset:49152
	ds_read_b128 v[4:7], v10 offset:61440
	s_waitcnt lgkmcnt(1)
	v_mfma_f32_32x32x16_bf16 v[16:31], v[0:3], v[112:115], v[16:31]
	v_or_b32_e32 v0, 0x100, v160
	v_xad_u32 v197, v0, v9, v8
	v_add_u32_e32 v10, 0, v197
	s_waitcnt lgkmcnt(0)
	v_mfma_f32_32x32x16_bf16 v[32:47], v[4:7], v[112:115], v[32:47]
	ds_read_b128 v[0:3], v10 offset:49152
	ds_read_b128 v[4:7], v10 offset:61440
	s_waitcnt lgkmcnt(1)
	v_mfma_f32_32x32x16_bf16 v[16:31], v[0:3], v[108:111], v[16:31]
	v_or_b32_e32 v0, 0x120, v160
	v_xad_u32 v196, v0, v9, v8
	v_add_u32_e32 v10, 0, v196
	ds_read_b128 v[0:3], v10 offset:49152
	s_waitcnt lgkmcnt(1)
	v_mfma_f32_32x32x16_bf16 v[32:47], v[4:7], v[108:111], v[32:47]
	ds_read_b128 v[4:7], v10 offset:61440
	s_waitcnt lgkmcnt(1)
	v_mfma_f32_32x32x16_bf16 v[16:31], v[0:3], v[104:107], v[16:31]
	v_or_b32_e32 v0, 0x140, v160
	v_xad_u32 v195, v0, v9, v8
	v_add_u32_e32 v10, 0, v195
	ds_read_b128 v[0:3], v10 offset:49152
	ds_read_b128 v[54:57], v10 offset:61440
	s_waitcnt lgkmcnt(2)
	v_mfma_f32_32x32x16_bf16 v[32:47], v[4:7], v[104:107], v[32:47]
	v_or_b32_e32 v4, 0x160, v160
	v_xad_u32 v194, v4, v9, v8
	v_add_u32_e32 v8, 0, v194
	ds_read_b128 v[4:7], v8 offset:49152
	ds_read_b128 v[58:61], v8 offset:61440
	s_waitcnt lgkmcnt(3)
; __device__ __forceinline__ void partialSM(f32x16& p0, f32x16& p1, float& m_reg, float& mn, float& alpha) {
;   constexpr float C = ASCALE * 1.4426950408889634f;
;   float pmax = p0[0]; for (int r = 1; r < 16; ++r) pmax = fmaxf(pmax, p0[r]); for (int r = 0; r < 16; ++r) pmax = fmaxf(pmax, p1[r]);
;   { auto rr = __builtin_amdgcn_permlane32_swap(__float_as_uint(pmax), __float_as_uint(pmax), false, false);
;     pmax = fmaxf(__uint_as_float(rr[0]), __uint_as_float(rr[1])); }
;   if (__builtin_expect(__all(pmax - m_reg <= THR / ASCALE), 1)) { mn = m_reg; alpha = 1.f; }
;   else { mn = fmaxf(m_reg, pmax); alpha = __builtin_amdgcn_exp2f((m_reg - mn) * C); m_reg = mn; }
;   float mnC = -mn * C;
;   for (int r = 0; r < 16; ++r) p0[r] = fmaf(p0[r], C, mnC); for (int r = 0; r < 16; ++r) p1[r] = fmaf(p1[r], C, mnC);
;   for (int r = 0; r < 16; ++r) p0[r] = __builtin_amdgcn_exp2f(p0[r]);
; }
; __device__ __forceinline__ void attn_body(const u16* __restrict__ Qb, const u16* __restrict__ Kh, const u16* __restrict__ Vh,
;                                           u16* __restrict__ Ob, int seq, int wvs) {
;     ...
;   float m_reg = -1e30f, l_reg = 0; f32x16 o[4] = {}; bf16x8 qr[12];
	v_mfma_f32_32x32x16_bf16 v[16:31], v[0:3], v[100:103], v[16:31]
	s_waitcnt lgkmcnt(1)
	v_mfma_f32_32x32x16_bf16 v[16:31], v[4:7], v[96:99], v[16:31]
	v_mov_b64_e32 v[0:1], s[12:13]
	v_mov_b64_e32 v[14:15], s[26:27]
	v_mov_b64_e32 v[2:3], s[14:15]
	v_mov_b64_e32 v[4:5], s[16:17]
	v_mov_b64_e32 v[6:7], s[18:19]
	v_mov_b64_e32 v[8:9], s[20:21]
	v_mov_b64_e32 v[10:11], s[22:23]
	v_mfma_f32_32x32x16_bf16 v[32:47], v[54:57], v[100:103], v[32:47]
	s_nop 3
	v_max_f32_e32 v70, v17, v17
	v_max_f32_e32 v71, v16, v16
	v_max_f32_e32 v70, v71, v70
	v_max3_f32 v54, v70, v18, v19
	v_max3_f32 v54, v54, v20, v21
	v_max3_f32 v54, v54, v22, v23
	v_max3_f32 v54, v54, v24, v25
	s_waitcnt lgkmcnt(0)
	v_mfma_f32_32x32x16_bf16 v[32:47], v[58:61], v[96:99], v[32:47]
	v_max3_f32 v54, v54, v26, v27
	v_max3_f32 v54, v54, v28, v29
	v_max3_f32 v54, v54, v30, v31
	v_mov_b64_e32 v[12:13], s[24:25]
	s_nop 7
	v_max3_f32 v54, v54, v32, v33
	v_max3_f32 v54, v54, v34, v35
	v_max3_f32 v54, v54, v36, v37
	v_max3_f32 v54, v54, v38, v39
	v_max3_f32 v54, v54, v40, v41
	v_max3_f32 v54, v54, v42, v43
	v_max3_f32 v54, v54, v44, v45
	v_max3_f32 v54, v54, v46, v47
	v_mov_b32_e32 v55, v54
	s_nop 1
	v_permlane32_swap_b32_e32 v54, v55
	v_max_f32_e32 v55, v55, v55
	v_max_f32_e32 v54, v54, v54
	v_max_f32_e32 v54, v54, v55
	v_add_f32_e32 v55, 0x7149f2ca, v54
	v_cmp_ge_f32_e32 vcc, s35, v55
	s_cmp_eq_u64 vcc, exec
	v_max_f32_e32 v54, 0xf149f2ca, v54
	s_cselect_b64 vcc, -1, 0
	v_mov_b32_e32 v55, 0xf149f2ca
	v_cndmask_b32_e32 v191, v54, v55, vcc
	v_sub_f32_e32 v56, 0xf149f2ca, v54
	v_mul_f32_e32 v54, 0xbdd53b94, v191
	v_fmamk_f32 v16, v16, 0x3dd53b94, v54
	v_exp_f32_e32 v218, v16
	v_fmamk_f32 v16, v17, 0x3dd53b94, v54
	v_exp_f32_e32 v220, v16
	v_fmamk_f32 v16, v18, 0x3dd53b94, v54
	v_exp_f32_e32 v221, v16
	v_fmamk_f32 v16, v19, 0x3dd53b94, v54
	v_exp_f32_e32 v222, v16
	v_fmamk_f32 v16, v20, 0x3dd53b94, v54
	v_exp_f32_e32 v223, v16
	v_fmamk_f32 v16, v21, 0x3dd53b94, v54
	v_exp_f32_e32 v225, v16
	v_fmamk_f32 v16, v22, 0x3dd53b94, v54
	v_exp_f32_e32 v224, v16
	v_fmamk_f32 v16, v23, 0x3dd53b94, v54
	v_exp_f32_e32 v226, v16
	v_fmamk_f32 v16, v24, 0x3dd53b94, v54
	v_exp_f32_e32 v211, v16
	v_fmamk_f32 v16, v25, 0x3dd53b94, v54
	v_exp_f32_e32 v212, v16
	v_fmamk_f32 v16, v26, 0x3dd53b94, v54
	v_exp_f32_e32 v213, v16
	v_fmamk_f32 v16, v27, 0x3dd53b94, v54
	v_exp_f32_e32 v215, v16
	v_fmamk_f32 v16, v28, 0x3dd53b94, v54
	v_exp_f32_e32 v214, v16
	v_fmamk_f32 v16, v29, 0x3dd53b94, v54
	v_exp_f32_e32 v216, v16
	v_fmamk_f32 v16, v30, 0x3dd53b94, v54
	v_exp_f32_e32 v217, v16
	v_or3_b32 v16, v68, v64, v62
	v_lshlrev_b32_e32 v16, 8, v16
	v_mul_f32_e32 v56, 0x3dd53b94, v56
	v_or3_b32 v16, v16, v66, v67
	v_mov_b32_e32 v17, v161
	v_exp_f32_e32 v56, v56
	v_bfe_u32 v252, v16, 10, 1
	v_bfe_u32 v253, v16, 11, 1
	v_xor_b32_e32 v252, v252, v253
	v_mul_u32_u24_e32 v252, 0xc00, v252
	v_xor_b32_e32 v16, v16, v252
	v_mov_b32_e32 v170, v16
	s_add_u32 s100, s80, s88
	s_addc_u32 s101, s81, s89
	s_add_u32 s100, s100, s72
	s_addc_u32 s101, s101, s73
	v_or_b32_e32 v16, v63, v64
	v_pk_fma_f32 v[144:145], v[46:47], s[68:69], v[54:55] op_sel_hi:[1,0,0]
	v_pk_fma_f32 v[146:147], v[44:45], s[68:69], v[54:55] op_sel_hi:[1,0,0]
	v_pk_fma_f32 v[148:149], v[42:43], s[68:69], v[54:55] op_sel_hi:[1,0,0]
	v_pk_fma_f32 v[150:151], v[40:41], s[68:69], v[54:55] op_sel_hi:[1,0,0]
	v_pk_fma_f32 v[152:153], v[38:39], s[68:69], v[54:55] op_sel_hi:[1,0,0]
	v_pk_fma_f32 v[154:155], v[36:37], s[68:69], v[54:55] op_sel_hi:[1,0,0]
	v_pk_fma_f32 v[156:157], v[34:35], s[68:69], v[54:55] op_sel_hi:[1,0,0]
	v_pk_fma_f32 v[158:159], v[32:33], s[68:69], v[54:55] op_sel_hi:[1,0,0]
	v_fmac_f32_e32 v54, 0x3dd53b94, v31
	v_or3_b32 v16, v16, v65, v62
	v_exp_f32_e32 v219, v54
	v_lshlrev_b32_e32 v16, 8, v16
	v_or3_b32 v16, v16, v66, v67
	v_cndmask_b32_e64 v208, v56, 1.0, vcc
	v_bfe_u32 v252, v16, 10, 1
	v_bfe_u32 v253, v16, 11, 1
	v_xor_b32_e32 v252, v252, v253
	v_mul_u32_u24_e32 v252, 0xc00, v252
	v_xor_b32_e32 v16, v16, v252
	v_mov_b32_e32 v169, v16
	v_mov_b64_e32 v[62:63], v[14:15]
	v_mov_b64_e32 v[46:47], v[14:15]
	v_mov_b64_e32 v[30:31], v[14:15]
	v_mov_b64_e32 v[60:61], v[12:13]
	v_mov_b64_e32 v[58:59], v[10:11]
	v_mov_b64_e32 v[56:57], v[8:9]
	v_mov_b64_e32 v[54:55], v[6:7]
	v_mov_b64_e32 v[52:53], v[4:5]
	v_mov_b64_e32 v[50:51], v[2:3]
	v_mov_b64_e32 v[48:49], v[0:1]
	v_mov_b64_e32 v[44:45], v[12:13]
	v_mov_b64_e32 v[42:43], v[10:11]
	v_mov_b64_e32 v[40:41], v[8:9]
	v_mov_b64_e32 v[38:39], v[6:7]
	v_mov_b64_e32 v[36:37], v[4:5]
	v_mov_b64_e32 v[34:35], v[2:3]
	v_mov_b64_e32 v[32:33], v[0:1]
	v_mov_b64_e32 v[28:29], v[12:13]
	v_mov_b64_e32 v[26:27], v[10:11]
	v_mov_b64_e32 v[24:25], v[8:9]
	v_mov_b64_e32 v[22:23], v[6:7]
	v_mov_b64_e32 v[20:21], v[4:5]
	v_mov_b64_e32 v[18:19], v[2:3]
	v_mov_b64_e32 v[16:17], v[0:1]

; __device__ __forceinline__ void partialSM(f32x16& p0, f32x16& p1, float& m_reg, float& mn, float& alpha) {
;     ...
;   for (int r = 0; r < 16; ++r) p0[r] = fmaf(p0[r], C, mnC); for (int r = 0; r < 16; ++r) p1[r] = fmaf(p1[r], C, mnC);
;   for (int r = 0; r < 16; ++r) p0[r] = __builtin_amdgcn_exp2f(p0[r]);
; }
; __device__ __forceinline__ void finishSM(f32x16& p0, f32x16& p1, float alpha, float& l_reg, bf16x8& pa0, bf16x8& pa1, bf16x8& pa2, bf16x8& pa3) {
;   for (int r = 0; r < 16; ++r) p1[r] = __builtin_amdgcn_exp2f(p1[r]);
;   float ps = 0; for (int r = 0; r < 16; ++r) ps += p0[r]; for (int r = 0; r < 16; ++r) ps += p1[r];
;   { auto rr = __builtin_amdgcn_permlane32_swap(__float_as_uint(ps), __float_as_uint(ps), false, false);
;     ps = __uint_as_float(rr[0]) + __uint_as_float(rr[1]); }
;   l_reg = l_reg * alpha + ps;
;     ...
;   PK4(p0, 0, pa0); PK4(p0, 8, pa1); PK4(p1, 0, pa2); PK4(p1, 8, pa3);
;     ...
; }
; template <int D0> __device__ __forceinline__ void pv_one(f32x16& od, int vb, bf16x8 pa0, bf16x8 pa1, bf16x8 pa2, bf16x8 pa3) {
;   const s16x4 l0 = tr_read<v_rd_off(D0, 0, 0)>(vb), h0 = tr_read<v_rd_off(D0, 0, 1)>(vb), l1 = tr_read<v_rd_off(D0, 1, 0)>(vb), h1 = tr_read<v_rd_off(D0, 1, 1)>(vb);
;   const s16x4 l2 = tr_read<v_rd_off(D0, 2, 0)>(vb), h2 = tr_read<v_rd_off(D0, 2, 1)>(vb), l3 = tr_read<v_rd_off(D0, 3, 0)>(vb), h3 = tr_read<v_rd_off(D0, 3, 1)>(vb);
;     ...
;   od = __builtin_amdgcn_mfma_f32_32x32x16_bf16(pa0, PK(l0, h0), od, 0, 0, 0);
;   od = __builtin_amdgcn_mfma_f32_32x32x16_bf16(pa1, PK(l1, h1), od, 0, 0, 0);
;   od = __builtin_amdgcn_mfma_f32_32x32x16_bf16(pa2, PK(l2, h2), od, 0, 0, 0);
;   od = __builtin_amdgcn_mfma_f32_32x32x16_bf16(pa3, PK(l3, h3), od, 0, 0, 0);
;     ...
; }
; __device__ __forceinline__ void pv_d0(f32x16* o, int vb, bf16x8 pa0, bf16x8 pa1, bf16x8 pa2, bf16x8 pa3) {
;   pv_one<0>(o[0], vb, pa0, pa1, pa2, pa3); pv_one<1>(o[1], vb, pa0, pa1, pa2, pa3); pv_one<2>(o[2], vb, pa0, pa1, pa2, pa3); pv_one<3>(o[3], vb, pa0, pa1, pa2, pa3);
.LBB0_376:
	v_cndmask_b32_e64 v97, v97, v191, s[8:9]
	s_waitcnt vmcnt(0) lgkmcnt(0)
	v_mul_f32_e32 v97, 0xbdd53b94, v97
	v_fmamk_f32 v80, v80, 0x3dd53b94, v97
	v_fmamk_f32 v81, v81, 0x3dd53b94, v97
	v_fmamk_f32 v82, v82, 0x3dd53b94, v97
	v_fmamk_f32 v83, v83, 0x3dd53b94, v97
	v_fmamk_f32 v84, v84, 0x3dd53b94, v97
	v_fmamk_f32 v85, v85, 0x3dd53b94, v97
	v_fmamk_f32 v86, v86, 0x3dd53b94, v97
	v_fmamk_f32 v87, v87, 0x3dd53b94, v97
	v_fmamk_f32 v88, v88, 0x3dd53b94, v97
	v_fmamk_f32 v89, v89, 0x3dd53b94, v97
	v_fmamk_f32 v90, v90, 0x3dd53b94, v97
	v_fmamk_f32 v91, v91, 0x3dd53b94, v97
	v_fmamk_f32 v92, v92, 0x3dd53b94, v97
	v_fmamk_f32 v93, v93, 0x3dd53b94, v97
	v_fmamk_f32 v94, v94, 0x3dd53b94, v97
	v_fmamk_f32 v95, v95, 0x3dd53b94, v97
	v_fmamk_f32 v64, v64, 0x3dd53b94, v97
	v_fmamk_f32 v65, v65, 0x3dd53b94, v97
	v_fmamk_f32 v66, v66, 0x3dd53b94, v97
	v_fmamk_f32 v67, v67, 0x3dd53b94, v97
	v_fmamk_f32 v68, v68, 0x3dd53b94, v97
	v_fmamk_f32 v69, v69, 0x3dd53b94, v97
	v_fmamk_f32 v70, v70, 0x3dd53b94, v97
	v_fmamk_f32 v71, v71, 0x3dd53b94, v97
	v_fmamk_f32 v72, v72, 0x3dd53b94, v97
	v_fmamk_f32 v73, v73, 0x3dd53b94, v97
	v_fmamk_f32 v74, v74, 0x3dd53b94, v97
	v_fmamk_f32 v75, v75, 0x3dd53b94, v97
	v_fmamk_f32 v76, v76, 0x3dd53b94, v97
	v_fmamk_f32 v77, v77, 0x3dd53b94, v97
	v_fmamk_f32 v78, v78, 0x3dd53b94, v97
	v_fmac_f32_e32 v97, 0x3dd53b94, v79
	v_exp_f32_e32 v79, v80
	v_exp_f32_e32 v98, v81
	v_exp_f32_e32 v82, v82
	v_exp_f32_e32 v83, v83
	v_exp_f32_e32 v84, v84
	v_exp_f32_e32 v85, v85
	v_exp_f32_e32 v86, v86
	v_exp_f32_e32 v87, v87
	v_exp_f32_e32 v88, v88
	v_exp_f32_e32 v89, v89
	v_exp_f32_e32 v90, v90
	v_exp_f32_e32 v91, v91
	v_exp_f32_e32 v92, v92
	v_exp_f32_e32 v93, v93
	v_exp_f32_e32 v94, v94
	v_exp_f32_e32 v95, v95
	s_barrier
	v_exp_f32_e32 v99, v68
	v_add_f32_e32 v68, 0, v79
	v_add_f32_e32 v68, v98, v68
	v_add_f32_e32 v68, v82, v68
	v_add_f32_e32 v68, v83, v68
	v_add_f32_e32 v68, v84, v68
	v_add_f32_e32 v68, v85, v68
	v_add_f32_e32 v68, v86, v68
	v_add_f32_e32 v68, v87, v68
	v_add_f32_e32 v68, v88, v68
	v_add_f32_e32 v68, v89, v68
	v_add_f32_e32 v68, v90, v68
	v_add_f32_e32 v68, v91, v68
	v_exp_f32_e32 v64, v64
	v_add_f32_e32 v68, v92, v68
	v_exp_f32_e32 v65, v65
	v_add_f32_e32 v68, v93, v68
	v_exp_f32_e32 v66, v66
	v_add_f32_e32 v68, v94, v68
	v_exp_f32_e32 v67, v67
	v_add_f32_e32 v68, v95, v68
	v_add_f32_e32 v68, v64, v68
	v_exp_f32_e32 v100, v69
	v_add_f32_e32 v68, v65, v68
	v_exp_f32_e32 v101, v70
	v_add_f32_e32 v68, v66, v68
	v_exp_f32_e32 v71, v71
	v_add_f32_e32 v68, v67, v68
	v_exp_f32_e32 v102, v72
	v_add_f32_e32 v68, v99, v68
	v_exp_f32_e32 v103, v73
	v_add_f32_e32 v68, v100, v68
	v_exp_f32_e32 v104, v74
	v_add_f32_e32 v68, v101, v68
	v_exp_f32_e32 v105, v75
	v_add_f32_e32 v68, v71, v68
	v_exp_f32_e32 v106, v76
	v_add_f32_e32 v68, v102, v68
	v_exp_f32_e32 v107, v77
	v_add_f32_e32 v68, v103, v68
	v_exp_f32_e32 v108, v78
	v_add_f32_e32 v68, v104, v68
	v_exp_f32_e32 v97, v97
	v_add_f32_e32 v68, v105, v68
	v_add_f32_e32 v68, v106, v68
	v_add_f32_e32 v68, v107, v68
	v_add_f32_e32 v68, v108, v68
	v_add_f32_e32 v80, v97, v68
	v_mov_b32_e32 v81, v80
	s_nop 1
	v_permlane32_swap_b32_e32 v80, v81
	v_cvt_pk_bf16_f32 v76, v79, v98
	v_cvt_pk_bf16_f32 v77, v82, v83
	v_cvt_pk_bf16_f32 v78, v84, v85
	v_cvt_pk_bf16_f32 v79, v86, v87
	v_cvt_pk_bf16_f32 v72, v88, v89
	v_cvt_pk_bf16_f32 v73, v90, v91
	v_cvt_pk_bf16_f32 v74, v92, v93
	v_cvt_pk_bf16_f32 v75, v94, v95
	v_cvt_pk_bf16_f32 v68, v64, v65
	v_cvt_pk_bf16_f32 v69, v66, v67
	v_cvt_pk_bf16_f32 v70, v99, v100
	v_cvt_pk_bf16_f32 v71, v101, v71
	v_cvt_pk_bf16_f32 v64, v102, v103
	v_cvt_pk_bf16_f32 v65, v104, v105
	v_cvt_pk_bf16_f32 v66, v106, v107
	v_cvt_pk_bf16_f32 v67, v108, v97
	v_add_u32_e32 v86, s16, v190
	ds_read_b64_tr_b16 v[82:83], v86
	ds_read_b64_tr_b16 v[84:85], v86 offset:2048
	s_waitcnt lgkmcnt(0)
	v_mfma_f32_32x32x16_bf16 v[0:15], v[76:79], v[82:85], v[0:15]
	ds_read_b64_tr_b16 v[82:83], v86 offset:4096
	ds_read_b64_tr_b16 v[84:85], v86 offset:6144
	s_waitcnt lgkmcnt(0)
	v_mfma_f32_32x32x16_bf16 v[0:15], v[72:75], v[82:85], v[0:15]
	ds_read_b64_tr_b16 v[82:83], v86 offset:8192
	ds_read_b64_tr_b16 v[84:85], v86 offset:10240
	s_waitcnt lgkmcnt(0)
	v_mfma_f32_32x32x16_bf16 v[0:15], v[68:71], v[82:85], v[0:15]
	ds_read_b64_tr_b16 v[82:83], v86 offset:12288
	ds_read_b64_tr_b16 v[84:85], v86 offset:14336
	s_waitcnt lgkmcnt(0)
	v_mfma_f32_32x32x16_bf16 v[0:15], v[64:67], v[82:85], v[0:15]
	ds_read_b64_tr_b16 v[82:83], v86 offset:512
	ds_read_b64_tr_b16 v[84:85], v86 offset:2560
	s_waitcnt lgkmcnt(0)
	v_mfma_f32_32x32x16_bf16 v[48:63], v[76:79], v[82:85], v[48:63]
	ds_read_b64_tr_b16 v[82:83], v86 offset:4608
	ds_read_b64_tr_b16 v[84:85], v86 offset:6656
	s_waitcnt lgkmcnt(0)
	v_mfma_f32_32x32x16_bf16 v[48:63], v[72:75], v[82:85], v[48:63]
	ds_read_b64_tr_b16 v[82:83], v86 offset:8704
	ds_read_b64_tr_b16 v[84:85], v86 offset:10752
	s_waitcnt lgkmcnt(0)
	v_mfma_f32_32x32x16_bf16 v[48:63], v[68:71], v[82:85], v[48:63]
	ds_read_b64_tr_b16 v[82:83], v86 offset:12800
	ds_read_b64_tr_b16 v[84:85], v86 offset:14848
	s_waitcnt lgkmcnt(0)
	v_mfma_f32_32x32x16_bf16 v[48:63], v[64:67], v[82:85], v[48:63]
	ds_read_b64_tr_b16 v[82:83], v86 offset:1024
	ds_read_b64_tr_b16 v[84:85], v86 offset:3072
	s_waitcnt lgkmcnt(0)
	v_mfma_f32_32x32x16_bf16 v[32:47], v[76:79], v[82:85], v[32:47]
	ds_read_b64_tr_b16 v[82:83], v86 offset:5120
	ds_read_b64_tr_b16 v[84:85], v86 offset:7168
	s_waitcnt lgkmcnt(0)
	v_mfma_f32_32x32x16_bf16 v[32:47], v[72:75], v[82:85], v[32:47]
	ds_read_b64_tr_b16 v[82:83], v86 offset:9216
	ds_read_b64_tr_b16 v[84:85], v86 offset:11264
	s_waitcnt lgkmcnt(0)
; __device__ __forceinline__ u16 f2bf(float x) { return (u16)(cvtpk(x, 0.f) & 0xffffu); }
; __device__ __forceinline__ int crow(int r, int hi) { return (r & 3) + 8 * (r >> 2) + 4 * hi; }
; __device__ __forceinline__ void attn_body(const u16* __restrict__ Qb, const u16* __restrict__ Kh, const u16* __restrict__ Vh,
;                                           u16* __restrict__ Ob, int seq, int wvs) {
;     ...
;   if (hi == 0) li_l[r32] = l_reg; asm volatile("s_waitcnt lgkmcnt(0)" ::: "memory");
;   float rli[16];
; #pragma unroll
;   for (int r = 0; r < 16; ++r) rli[r] = __builtin_amdgcn_rcpf(li_l[crow(r, hi)]);
;   u16* Ow = Ob + (long)(wid * QBLK) * DM;
; #pragma unroll
;   for (int r = 0; r < 16; ++r) { int orow = crow(r, hi);
; #pragma unroll
;     for (int d0 = 0; d0 < 4; ++d0) Ow[(long)orow * DM + d0 * 32 + r32] = f2bf(o[d0][r] * rli[r]); }
	v_mfma_f32_32x32x16_bf16 v[32:47], v[68:71], v[82:85], v[32:47]
	ds_read_b64_tr_b16 v[82:83], v86 offset:13312
	ds_read_b64_tr_b16 v[84:85], v86 offset:15360
	s_waitcnt lgkmcnt(0)
	v_mfma_f32_32x32x16_bf16 v[32:47], v[64:67], v[82:85], v[32:47]
	ds_read_b64_tr_b16 v[82:83], v86 offset:1536
	ds_read_b64_tr_b16 v[84:85], v86 offset:3584
	s_waitcnt lgkmcnt(0)
	v_mfma_f32_32x32x16_bf16 v[16:31], v[76:79], v[82:85], v[16:31]
	ds_read_b64_tr_b16 v[76:77], v86 offset:5632
	ds_read_b64_tr_b16 v[78:79], v86 offset:7680
	s_waitcnt lgkmcnt(0)
	v_mfma_f32_32x32x16_bf16 v[16:31], v[72:75], v[76:79], v[16:31]
	ds_read_b64_tr_b16 v[72:73], v86 offset:9728
	ds_read_b64_tr_b16 v[74:75], v86 offset:11776
	s_waitcnt lgkmcnt(0)
	v_mfma_f32_32x32x16_bf16 v[16:31], v[68:71], v[72:75], v[16:31]
	ds_read_b64_tr_b16 v[68:69], v86 offset:13824
	ds_read_b64_tr_b16 v[70:71], v86 offset:15872
	s_waitcnt lgkmcnt(0)
	v_mfma_f32_32x32x16_bf16 v[16:31], v[64:67], v[68:71], v[16:31]
	s_and_saveexec_b64 s[4:5], s[6:7]
	v_add_f32_e32 v64, v112, v113
	v_fmac_f32_e32 v64, v189, v176
	v_add_f32_e32 v65, v80, v81
	v_fmac_f32_e32 v65, v64, v96
	ds_write_b32 v188, v65
	s_or_b64 exec, exec, s[4:5]
	s_waitcnt lgkmcnt(0)
	v_add_u32_e32 v72, v165, v160
	ds_read_b128 v[64:67], v72
	ds_read_b128 v[68:71], v72 offset:32
	v_ashrrev_i32_e32 v165, 31, v164
	v_readlane_b32 s4, v254, 43
	v_readlane_b32 s5, v254, 44
	s_waitcnt lgkmcnt(0)
	v_rcp_f32_e32 v73, v64
	v_rcp_f32_e32 v74, v65
	v_rcp_f32_e32 v75, v66
	v_rcp_f32_e32 v76, v67
	ds_read_b128 v[64:67], v72 offset:64
	v_rcp_f32_e32 v77, v68
	v_rcp_f32_e32 v78, v69
	v_rcp_f32_e32 v79, v70
	v_rcp_f32_e32 v80, v71
	ds_read_b128 v[68:71], v72 offset:96
	s_waitcnt lgkmcnt(0)
	v_rcp_f32_e32 v72, v64
	v_rcp_f32_e32 v81, v65
	v_lshlrev_b64 v[64:65], 12, v[164:165]
	v_lshl_add_u64 v[64:65], s[4:5], 0, v[64:65]
	v_lshlrev_b32_e32 v160, 1, v187
	v_rcp_f32_e32 v82, v66
	v_rcp_f32_e32 v83, v67
	v_lshlrev_b32_e32 v66, 14, v186
	v_lshl_add_u64 v[64:65], v[64:65], 0, v[160:161]
	v_mov_b32_e32 v67, v161
	v_mul_f32_e32 v0, v0, v73
	v_lshl_add_u64 v[64:65], v[64:65], 0, v[66:67]
	v_cvt_pk_bf16_f32 v0, v0, s0
	flat_store_short v[64:65], v0
	v_mul_f32_e32 v0, v48, v73
	v_cvt_pk_bf16_f32 v0, v0, s0
	flat_store_short v[64:65], v0 offset:64
	v_mul_f32_e32 v0, v32, v73
	v_cvt_pk_bf16_f32 v0, v0, s0
	flat_store_short v[64:65], v0 offset:128
	v_mul_f32_e32 v0, v16, v73
	v_cvt_pk_bf16_f32 v0, v0, s0
	flat_store_short v[64:65], v0 offset:192
	v_mul_f32_e32 v0, v1, v74
	s_movk_i32 s4, 0x1000
	v_cvt_pk_bf16_f32 v16, v0, s0
	v_add_co_u32_e32 v0, vcc, s4, v64
	s_movk_i32 s4, 0x2000
	s_nop 0
	v_addc_co_u32_e32 v1, vcc, 0, v65, vcc
	flat_store_short v[0:1], v16
	v_mul_f32_e32 v16, v49, v74
	v_cvt_pk_bf16_f32 v16, v16, s0
	flat_store_short v[0:1], v16 offset:64
	v_mul_f32_e32 v16, v33, v74
	v_cvt_pk_bf16_f32 v16, v16, s0
	flat_store_short v[0:1], v16 offset:128
	v_mul_f32_e32 v16, v17, v74
	v_cvt_pk_bf16_f32 v16, v16, s0
	flat_store_short v[0:1], v16 offset:192
	v_mul_f32_e32 v0, v2, v75
	v_cvt_pk_bf16_f32 v2, v0, s0
	v_add_co_u32_e32 v0, vcc, s4, v64
	s_movk_i32 s4, 0x3000
	s_nop 0
	v_addc_co_u32_e32 v1, vcc, 0, v65, vcc
	flat_store_short v[0:1], v2
	v_mul_f32_e32 v2, v50, v75
	v_cvt_pk_bf16_f32 v2, v2, s0
	flat_store_short v[0:1], v2 offset:64
	v_mul_f32_e32 v2, v34, v75
	v_cvt_pk_bf16_f32 v2, v2, s0
	flat_store_short v[0:1], v2 offset:128
	v_mul_f32_e32 v2, v18, v75
	v_cvt_pk_bf16_f32 v2, v2, s0
	flat_store_short v[0:1], v2 offset:192
	v_mul_f32_e32 v0, v3, v76
	v_cvt_pk_bf16_f32 v2, v0, s0
	v_add_co_u32_e32 v0, vcc, s4, v64
	s_mov_b32 s4, 0x8000
	s_nop 0
	v_addc_co_u32_e32 v1, vcc, 0, v65, vcc
	flat_store_short v[0:1], v2
	v_mul_f32_e32 v2, v51, v76
	v_cvt_pk_bf16_f32 v2, v2, s0
	flat_store_short v[0:1], v2 offset:64
	v_mul_f32_e32 v2, v35, v76
	v_cvt_pk_bf16_f32 v2, v2, s0
	flat_store_short v[0:1], v2 offset:128
	v_mul_f32_e32 v2, v19, v76
	v_cvt_pk_bf16_f32 v2, v2, s0
	flat_store_short v[0:1], v2 offset:192
	v_mul_f32_e32 v0, v4, v77
	v_cvt_pk_bf16_f32 v2, v0, s0
	v_add_co_u32_e32 v0, vcc, s4, v64
	s_mov_b32 s4, 0x9000
	s_nop 0
	v_addc_co_u32_e32 v1, vcc, 0, v65, vcc
	flat_store_short v[0:1], v2
	v_mul_f32_e32 v2, v52, v77
	v_cvt_pk_bf16_f32 v2, v2, s0
	flat_store_short v[0:1], v2 offset:64
	v_mul_f32_e32 v2, v36, v77
	v_cvt_pk_bf16_f32 v2, v2, s0
	flat_store_short v[0:1], v2 offset:128
	v_mul_f32_e32 v2, v20, v77
	v_cvt_pk_bf16_f32 v2, v2, s0
	flat_store_short v[0:1], v2 offset:192
	v_mul_f32_e32 v0, v5, v78
	v_cvt_pk_bf16_f32 v2, v0, s0
	v_add_co_u32_e32 v0, vcc, s4, v64
	s_mov_b32 s4, 0xa000
	s_nop 0
	v_addc_co_u32_e32 v1, vcc, 0, v65, vcc
	flat_store_short v[0:1], v2
	v_mul_f32_e32 v2, v53, v78
	v_cvt_pk_bf16_f32 v2, v2, s0
	flat_store_short v[0:1], v2 offset:64
	v_mul_f32_e32 v2, v37, v78
	v_cvt_pk_bf16_f32 v2, v2, s0
	flat_store_short v[0:1], v2 offset:128
	v_mul_f32_e32 v2, v21, v78
	v_cvt_pk_bf16_f32 v2, v2, s0
	flat_store_short v[0:1], v2 offset:192
	v_mul_f32_e32 v0, v6, v79
	v_cvt_pk_bf16_f32 v2, v0, s0
; __device__ __forceinline__ u16 f2bf(float x) { return (u16)(cvtpk(x, 0.f) & 0xffffu); }
; __device__ __forceinline__ int crow(int r, int hi) { return (r & 3) + 8 * (r >> 2) + 4 * hi; }
; __device__ __forceinline__ void attn_body(const u16* __restrict__ Qb, const u16* __restrict__ Kh, const u16* __restrict__ Vh,
;                                           u16* __restrict__ Ob, int seq, int wvs) {
;     ...
;   u16* Ow = Ob + (long)(wid * QBLK) * DM;
; #pragma unroll
;   for (int r = 0; r < 16; ++r) { int orow = crow(r, hi);
; #pragma unroll
;     for (int d0 = 0; d0 < 4; ++d0) Ow[(long)orow * DM + d0 * 32 + r32] = f2bf(o[d0][r] * rli[r]); }
	v_add_co_u32_e32 v0, vcc, s4, v64
	s_mov_b32 s4, 0xb000
	s_nop 0
	v_addc_co_u32_e32 v1, vcc, 0, v65, vcc
	flat_store_short v[0:1], v2
	v_mul_f32_e32 v2, v54, v79
	v_cvt_pk_bf16_f32 v2, v2, s0
	flat_store_short v[0:1], v2 offset:64
	v_mul_f32_e32 v2, v38, v79
	v_cvt_pk_bf16_f32 v2, v2, s0
	flat_store_short v[0:1], v2 offset:128
	v_mul_f32_e32 v2, v22, v79
	v_cvt_pk_bf16_f32 v2, v2, s0
	flat_store_short v[0:1], v2 offset:192
	v_mul_f32_e32 v0, v7, v80
	v_cvt_pk_bf16_f32 v2, v0, s0
	v_add_co_u32_e32 v0, vcc, s4, v64
	s_mov_b32 s4, 0x10000
	s_nop 0
	v_addc_co_u32_e32 v1, vcc, 0, v65, vcc
	flat_store_short v[0:1], v2
	v_mul_f32_e32 v2, v55, v80
	v_cvt_pk_bf16_f32 v2, v2, s0
	flat_store_short v[0:1], v2 offset:64
	v_mul_f32_e32 v2, v39, v80
	v_cvt_pk_bf16_f32 v2, v2, s0
	flat_store_short v[0:1], v2 offset:128
	v_mul_f32_e32 v2, v23, v80
	v_cvt_pk_bf16_f32 v2, v2, s0
	flat_store_short v[0:1], v2 offset:192
	v_mul_f32_e32 v0, v8, v72
	v_cvt_pk_bf16_f32 v2, v0, s0
	v_add_co_u32_e32 v0, vcc, s4, v64
	s_mov_b32 s4, 0x11000
	s_nop 0
	v_addc_co_u32_e32 v1, vcc, 0, v65, vcc
	flat_store_short v[0:1], v2
	v_mul_f32_e32 v2, v56, v72
	v_cvt_pk_bf16_f32 v2, v2, s0
	flat_store_short v[0:1], v2 offset:64
	v_mul_f32_e32 v2, v40, v72
	v_cvt_pk_bf16_f32 v2, v2, s0
	flat_store_short v[0:1], v2 offset:128
	v_mul_f32_e32 v2, v24, v72
	v_cvt_pk_bf16_f32 v2, v2, s0
	flat_store_short v[0:1], v2 offset:192
	v_mul_f32_e32 v0, v9, v81
	v_cvt_pk_bf16_f32 v2, v0, s0
	v_add_co_u32_e32 v0, vcc, s4, v64
	s_mov_b32 s4, 0x12000
	s_nop 0
	v_addc_co_u32_e32 v1, vcc, 0, v65, vcc
	flat_store_short v[0:1], v2
	v_mul_f32_e32 v2, v57, v81
	v_cvt_pk_bf16_f32 v2, v2, s0
	flat_store_short v[0:1], v2 offset:64
	v_mul_f32_e32 v2, v41, v81
	v_cvt_pk_bf16_f32 v2, v2, s0
	flat_store_short v[0:1], v2 offset:128
	v_mul_f32_e32 v2, v25, v81
	v_cvt_pk_bf16_f32 v2, v2, s0
	flat_store_short v[0:1], v2 offset:192
	v_mul_f32_e32 v0, v10, v82
	v_cvt_pk_bf16_f32 v2, v0, s0
	v_add_co_u32_e32 v0, vcc, s4, v64
	s_mov_b32 s4, 0x13000
	s_nop 0
	v_addc_co_u32_e32 v1, vcc, 0, v65, vcc
	flat_store_short v[0:1], v2
	v_mul_f32_e32 v2, v58, v82
	v_cvt_pk_bf16_f32 v2, v2, s0
	flat_store_short v[0:1], v2 offset:64
	v_mul_f32_e32 v2, v42, v82
	v_cvt_pk_bf16_f32 v2, v2, s0
	flat_store_short v[0:1], v2 offset:128
	v_mul_f32_e32 v2, v26, v82
	v_cvt_pk_bf16_f32 v2, v2, s0
	flat_store_short v[0:1], v2 offset:192
	v_mul_f32_e32 v0, v11, v83
	v_cvt_pk_bf16_f32 v2, v0, s0
	v_add_co_u32_e32 v0, vcc, s4, v64
	v_rcp_f32_e32 v68, v68
	s_nop 0
	v_addc_co_u32_e32 v1, vcc, 0, v65, vcc
	flat_store_short v[0:1], v2
	v_mul_f32_e32 v2, v59, v83
	v_cvt_pk_bf16_f32 v2, v2, s0
	flat_store_short v[0:1], v2 offset:64
	v_mul_f32_e32 v2, v43, v83
	v_cvt_pk_bf16_f32 v2, v2, s0
	flat_store_short v[0:1], v2 offset:128
	v_mul_f32_e32 v2, v27, v83
	v_cvt_pk_bf16_f32 v2, v2, s0
	flat_store_short v[0:1], v2 offset:192
	v_mul_f32_e32 v0, v12, v68
	s_mov_b32 s4, 0x18000
	v_cvt_pk_bf16_f32 v2, v0, s0
	v_add_co_u32_e32 v0, vcc, s4, v64
	v_rcp_f32_e32 v69, v69
	s_nop 0
	v_addc_co_u32_e32 v1, vcc, 0, v65, vcc
	flat_store_short v[0:1], v2
	v_mul_f32_e32 v2, v60, v68
	v_cvt_pk_bf16_f32 v2, v2, s0
	flat_store_short v[0:1], v2 offset:64
	v_mul_f32_e32 v2, v44, v68
	v_cvt_pk_bf16_f32 v2, v2, s0
	flat_store_short v[0:1], v2 offset:128
	v_mul_f32_e32 v2, v28, v68
	v_cvt_pk_bf16_f32 v2, v2, s0
	flat_store_short v[0:1], v2 offset:192
	v_mul_f32_e32 v0, v13, v69
	s_mov_b32 s4, 0x19000
	v_cvt_pk_bf16_f32 v2, v0, s0
	v_add_co_u32_e32 v0, vcc, s4, v64
	v_rcp_f32_e32 v70, v70
	s_nop 0
	v_addc_co_u32_e32 v1, vcc, 0, v65, vcc
	flat_store_short v[0:1], v2
	v_mul_f32_e32 v2, v61, v69
	v_cvt_pk_bf16_f32 v2, v2, s0
	flat_store_short v[0:1], v2 offset:64
	v_mul_f32_e32 v2, v45, v69
	v_cvt_pk_bf16_f32 v2, v2, s0
	flat_store_short v[0:1], v2 offset:128
	v_mul_f32_e32 v2, v29, v69
	v_cvt_pk_bf16_f32 v2, v2, s0
	flat_store_short v[0:1], v2 offset:192
	v_mul_f32_e32 v0, v14, v70
	s_mov_b32 s4, 0x1a000
	v_cvt_pk_bf16_f32 v2, v0, s0
	v_add_co_u32_e32 v0, vcc, s4, v64
	v_rcp_f32_e32 v71, v71
	s_nop 0
	v_addc_co_u32_e32 v1, vcc, 0, v65, vcc
	flat_store_short v[0:1], v2
	v_mul_f32_e32 v2, v62, v70
	v_cvt_pk_bf16_f32 v2, v2, s0
	flat_store_short v[0:1], v2 offset:64
	v_mul_f32_e32 v2, v46, v70
	v_cvt_pk_bf16_f32 v2, v2, s0
	flat_store_short v[0:1], v2 offset:128
	v_mul_f32_e32 v2, v30, v70
	v_cvt_pk_bf16_f32 v2, v2, s0
	flat_store_short v[0:1], v2 offset:192
	v_mul_f32_e32 v0, v15, v71
	s_mov_b32 s4, 0x1b000
	v_cvt_pk_bf16_f32 v2, v0, s0
	v_add_co_u32_e32 v0, vcc, s4, v64
	s_add_i32 s23, s41, 1
	s_nop 0
	v_addc_co_u32_e32 v1, vcc, 0, v65, vcc
	flat_store_short v[0:1], v2
	v_mul_f32_e32 v2, v63, v71
	v_cvt_pk_bf16_f32 v2, v2, s0
	flat_store_short v[0:1], v2 offset:64
	v_mul_f32_e32 v2, v47, v71
	v_cvt_pk_bf16_f32 v2, v2, s0
	flat_store_short v[0:1], v2 offset:128
	v_mul_f32_e32 v2, v31, v71
	v_cvt_pk_bf16_f32 v2, v2, s0
	s_mov_b64 s[24:25], 0
	flat_store_short v[0:1], v2 offset:192
	s_setprio 0
	s_cmp_eq_u32 s23, s92
	s_cbranch_scc0 .LBB0_768
	s_branch .LBB0_245
